# ATT phase: one static s_setprio 1 for waves 4-7 (younger half) for the whole phase
# speedup vs baseline: 1.0008x; 1.0008x over previous
; #define LAUNDER() int tid = tid0; asm volatile("" : "+v"(tid)); int wg = blockIdx.x; asm volatile("" : "+s"(wg)); const int lane = tid & 63, wave = __builtin_amdgcn_readfirstlane(tid >> 6), gw = wg * NWAVES + wave, NGW = G * NWAVES; (void)lane; (void)wave; (void)gw; (void)NGW
; __global__ void __launch_bounds__(NTHR, 2) fwd_kernel(Args a) {
;     ...
;         for (int stage = 0; stage < 2; ++stage) {
;         bool mla_now; { int wgs = blockIdx.x; asm volatile("" : "+s"(wgs)); mla_now = (stage == 0) != ((wgs & ATT_SWAP_MASK) != 0); }
;         if (mla_now) { LAUNDER();
.LBB0_825:
	v_readfirstlane_b32 s101, v0
	s_nop 3
	s_bfe_u32 s101, s101, 0x10008
	s_cmp_eq_u32 s101, 1
	s_cbranch_scc0 .Latt_prio_done
	s_setprio 1

; __device__ __forceinline__ unsigned xb_add(unsigned* p, unsigned v) { return __hip_atomic_fetch_add(p, v, __ATOMIC_RELAXED, __HIP_MEMORY_SCOPE_AGENT); }
; __device__ __forceinline__ void xcd_barrier(const XcdBarrier& b) {
;     asm volatile("s_waitcnt vmcnt(0)" ::: "memory");
;     __syncthreads();
;     if (threadIdx.x == 0) {
;         unsigned* bar = b.bar;
;         __builtin_amdgcn_s_waitcnt(0);
;         unsigned nloc = b.st[0], nx = b.st[1];
;         if (nloc == 0u) { xcd_barrier_complete(bar, b.x, nloc, nx); b.st[0] = nloc; b.st[1] = nx; }
;         const unsigned old = xb_add(&bar[XB_XSUB(b.x)], 1u);
.LBB0_980:
	s_setprio 0
	v_readlane_b32 s10, v252, 28
	s_waitcnt vmcnt(0)
	s_barrier
	s_mov_b64 s[2:3], exec
	v_readlane_b32 s4, v252, 29
	v_readlane_b32 s5, v252, 30
	v_readlane_b32 s50, v254, 39
	s_and_b64 s[4:5], s[2:3], s[4:5]
	v_readlane_b32 s51, v254, 40
	v_readlane_b32 s53, v254, 42
	s_mov_b32 s96, 0x70000
	s_mov_b32 s97, 0x2f800000
	s_mov_b32 s48, s46
	s_mov_b64 exec, s[4:5]
	s_cbranch_execz .LBB0_1032
	v_readlane_b32 s4, v254, 15
	s_waitcnt vmcnt(0) expcnt(0) lgkmcnt(0)
	s_nop 0
	v_mov_b32_e32 v1, s4
	ds_read_b32 v3, v1
	v_readlane_b32 s4, v254, 16
	s_waitcnt lgkmcnt(0)
	v_cmp_ne_u32_e32 vcc, 0, v3
	v_mov_b32_e32 v1, s4
	ds_read_b32 v2, v1
	s_cbranch_vccnz .LBB0_996
	v_readlane_b32 s6, v252, 24
	v_readlane_b32 s7, v252, 25
	s_load_dwordx2 s[4:5], s[6:7], 0x4
	s_mov_b32 s12, 1
	s_waitcnt lgkmcnt(0)
	s_mul_i32 s11, s4, s21
	s_mul_i32 s11, s11, s5
	s_branch .LBB0_984

; __global__ void __launch_bounds__(NTHR, 2) fwd_kernel(Args a) {
	.amdhsa_kernel _Z10fwd_kernel4Args
		.amdhsa_group_segment_fixed_size 0
		.amdhsa_private_segment_fixed_size 0
		.amdhsa_kernarg_size 432
		.amdhsa_user_sgpr_count 2
		.amdhsa_user_sgpr_dispatch_ptr 0
		.amdhsa_user_sgpr_queue_ptr 0
		.amdhsa_user_sgpr_kernarg_segment_ptr 1
		.amdhsa_user_sgpr_dispatch_id 0
		.amdhsa_user_sgpr_kernarg_preload_length 0
		.amdhsa_user_sgpr_kernarg_preload_offset 0
		.amdhsa_user_sgpr_private_segment_size 0
		.amdhsa_uses_dynamic_stack 0
		.amdhsa_enable_private_segment 0
		.amdhsa_system_sgpr_workgroup_id_x 1
		.amdhsa_system_sgpr_workgroup_id_y 0
		.amdhsa_system_sgpr_workgroup_id_z 0
		.amdhsa_system_sgpr_workgroup_info 0
		.amdhsa_system_vgpr_workitem_id 0
		.amdhsa_next_free_vgpr 256
		.amdhsa_next_free_sgpr 102
		.amdhsa_accum_offset 256
		.amdhsa_reserve_vcc 1
		.amdhsa_float_round_mode_32 0
		.amdhsa_float_round_mode_16_64 0
		.amdhsa_float_denorm_mode_32 3
		.amdhsa_float_denorm_mode_16_64 3
		.amdhsa_dx10_clamp 1
		.amdhsa_ieee_mode 1
		.amdhsa_fp16_overflow 0
		.amdhsa_tg_split 0
		.amdhsa_exception_fp_ieee_invalid_op 0
		.amdhsa_exception_fp_denorm_src 0
		.amdhsa_exception_fp_ieee_div_zero 0
		.amdhsa_exception_fp_ieee_overflow 0
		.amdhsa_exception_fp_ieee_underflow 0
		.amdhsa_exception_fp_ieee_inexact 0
		.amdhsa_exception_int_div_zero 0
	.end_amdhsa_kernel

; __global__ void __launch_bounds__(NTHR, 2) fwd_kernel(Args a) {
amdhsa.kernels:
  - .agpr_count:     0
    .args:
      - .offset:         0
        .size:           176
        .value_kind:     by_value
      - .offset:         176
        .size:           4
        .value_kind:     hidden_block_count_x
      - .offset:         180
        .size:           4
        .value_kind:     hidden_block_count_y
      - .offset:         184
        .size:           4
        .value_kind:     hidden_block_count_z
      - .offset:         188
        .size:           2
        .value_kind:     hidden_group_size_x
      - .offset:         190
        .size:           2
        .value_kind:     hidden_group_size_y
      - .offset:         192
        .size:           2
        .value_kind:     hidden_group_size_z
      - .offset:         194
        .size:           2
        .value_kind:     hidden_remainder_x
      - .offset:         196
        .size:           2
        .value_kind:     hidden_remainder_y
      - .offset:         198
        .size:           2
        .value_kind:     hidden_remainder_z
      - .offset:         216
        .size:           8
        .value_kind:     hidden_global_offset_x
      - .offset:         224
        .size:           8
        .value_kind:     hidden_global_offset_y
      - .offset:         232
        .size:           8
        .value_kind:     hidden_global_offset_z
      - .offset:         240
        .size:           2
        .value_kind:     hidden_grid_dims
      - .offset:         296
        .size:           4
        .value_kind:     hidden_dynamic_lds_size
    .group_segment_fixed_size: 0
    .kernarg_segment_align: 8
    .kernarg_segment_size: 432
    .language:       OpenCL C
    .language_version:
      - 2
      - 0
    .max_flat_workgroup_size: 512
    .name:           _Z10fwd_kernel4Args
    .private_segment_fixed_size: 0
    .sgpr_count:     108
    .sgpr_spill_count: 245
    .symbol:         _Z10fwd_kernel4Args.kd
    .uniform_work_group_size: 1
    .uses_dynamic_stack: false
    .vgpr_count:     256
    .vgpr_spill_count: 0
    .wavefront_size: 64
